# out-proj K-loop body shifted by 4 bytes (unexecuted pads): code-placement trial
# speedup vs baseline: 1.0032x; 1.0032x over previous
; #define RAW_BARRIER() do { asm volatile("s_waitcnt lgkmcnt(0)" ::: "memory"); __builtin_amdgcn_s_barrier(); } while (0)
; template <int WM, class Epi>
; DI void gemm_mfma(const bf16_t* __restrict__ A, const bf16_t* __restrict__ Bt, int Arows, int Brows, int MT, int NT, unsigned char* smem, int bid, int nb, int wave, Epi epi) {
;     ...
;   for (int li = l0; li < per; li += lstep) {
;     const int wi = xq * per + li;
;     const int patch = wi / (PM * PN), within = wi % (PM * PN);
;     const int mt = epi.mt_of((patch / NPN) * PM + within / PN), nt = (patch % NPN) * PN + within % PN;
;     f32x16 acc[WM][2];
; #pragma unroll
;     for (int a = 0; a < WM; ++a)
; #pragma unroll
;       for (int b = 0; b < 2; ++b)
; #pragma unroll
;         for (int i = 0; i < 16; ++i) acc[a][b][i] = 0.f;
;     constexpr int NAW = NA / 4;
;     const int wvu = __builtin_amdgcn_readfirstlane(wv);
;     const unsigned voff = (unsigned)((lrow * 32 + ((lpc ^ ((lrow >> 2) & 3)) << 3)) * 2);
;     const char* abase = (const char*)(A + (size_t)(mt * BMROWS + wvu * NAW * 16) * 32);
;     const char* bbase = (const char*)(Bt + (size_t)(nt * 128 + wvu * 2 * 16) * 32);
;     const size_t astep = (size_t)Arows * 64, bstep = (size_t)Brows * 64;
;     auto issue = [&](int kt, int buf) {
; #pragma unroll
;       for (int i = 0; i < NAW; ++i)
;         __builtin_amdgcn_global_load_lds((const unsigned*)(abase + kt * astep + i * 1024 + voff),
;                                          (__attribute__((address_space(3))) unsigned*)(smem + buf * STAGE + (wvu * NAW + i) * 1024), 16, 0, 0);
; #pragma unroll
;       for (int i = 0; i < 2; ++i)
;         __builtin_amdgcn_global_load_lds((const unsigned*)(bbase + kt * bstep + i * 1024 + voff),
;                                          (__attribute__((address_space(3))) unsigned*)(smem + buf * STAGE + A_BYTES + (wvu * 2 + i) * 1024), 16, 0, 0);
;     };
;     RAW_BARRIER();
;     constexpr int NST = (WM == 2) ? 4 : 3;
;     constexpr int NKT = K / 32;
; #pragma unroll
;     for (int s = 0; s < NST - 1; ++s) issue(s, s);
;     bf16x8 fa0[WM], fb0[2], fa1[WM], fb1[2];
; #pragma unroll
;     for (int mi = 0; mi < WM; ++mi) { fa0[mi] = bf16x8{0, 0, 0, 0, 0, 0, 0, 0}; fa1[mi] = fa0[mi]; }
;     fb0[0] = bf16x8{0, 0, 0, 0, 0, 0, 0, 0}; fb0[1] = fb0[0]; fb1[0] = fb0[0]; fb1[1] = fb0[0];
.LBB0_1054:
	v_readlane_b32 s4, v254, 4
	s_add_i32 s4, s24, s4
	s_ashr_i32 s5, s4, 31
	s_lshr_b32 s5, s5, 26
	s_add_i32 s5, s4, s5
	s_ashr_i32 s6, s5, 6
	s_and_b32 s5, s5, 0xffc0
	s_sub_i32 s4, s4, s5
	s_lshl_b32 s5, s6, 3
	s_bfe_i32 s6, s4, 0x80000
	s_bfe_u32 s6, s6, 0x3000c
	s_add_i32 s6, s4, s6
	s_bfe_i32 s7, s6, 0x80000
	s_sext_i32_i16 s7, s7
	s_ashr_i32 s7, s7, 3
	s_add_i32 s5, s5, s7
	s_lshr_b32 s5, s5, 3
	s_mul_i32 s5, s5, 9
	s_and_b32 s7, s7, 7
	s_add_i32 s7, s7, s5
	s_and_b32 s5, s6, 0xf8
	s_lshl_b32 s25, s7, 8
	s_sub_i32 s4, s4, s5
	v_readfirstlane_b32 s28, v154
	s_sext_i32_i8 s8, s4
	s_addk_i32 s25, 0x100
	s_lshl_b32 s4, s28, 6
	s_add_i32 s4, s25, s4
	s_ashr_i32 s5, s4, 31
	s_lshl_b64 s[6:7], s[4:5], 6
	s_add_u32 s4, s2, s6
	s_addc_u32 s5, s10, s7
	s_lshl_b32 s26, s8, 7
	s_lshl_b32 s8, s28, 5
	s_add_i32 s8, s26, s8
	s_ashr_i32 s9, s8, 31
	s_lshl_b64 s[8:9], s[8:9], 6
	s_add_u32 s30, s11, s8
	s_addc_u32 s31, s12, s9
	s_lshl_b32 s27, s28, 12
	v_lshl_add_u64 v[0:1], s[4:5], 0, v[160:161]
	s_mov_b32 m0, s27
	s_mov_b64 s[4:5], 0x400
	s_waitcnt lgkmcnt(0)
	s_barrier
	global_load_lds_dwordx4 v[0:1], off
	v_lshl_add_u64 v[2:3], v[0:1], 0, s[4:5]
	s_or_b32 m0, s27, 0x400
	s_mov_b64 s[34:35], 0x800
	global_load_lds_dwordx4 v[2:3], off
	v_lshl_add_u64 v[2:3], v[0:1], 0, s[34:35]
	s_or_b32 m0, s27, 0x800
	s_mov_b64 s[34:35], 0xc00
	s_lshl_b32 s28, s28, 11
	global_load_lds_dwordx4 v[2:3], off
	v_lshl_add_u64 v[2:3], v[0:1], 0, s[34:35]
	s_or_b32 m0, s27, 0xc00
	v_mov_b32_e32 v128, 0
	global_load_lds_dwordx4 v[2:3], off
	v_lshl_add_u64 v[2:3], s[30:31], 0, v[160:161]
	s_add_i32 m0, s28, 0x4000
	v_lshl_add_u64 v[4:5], v[2:3], 0, s[4:5]
	global_load_lds_dwordx4 v[2:3], off
	s_add_i32 m0, s28, 0x4400
	s_mov_b64 s[4:5], 0x120000
	global_load_lds_dwordx4 v[4:5], off
	v_lshl_add_u64 v[4:5], v[0:1], 0, s[4:5]
	s_add_i32 m0, s27, 0x6000
	s_mov_b64 s[4:5], 0x120400
	global_load_lds_dwordx4 v[4:5], off
	v_lshl_add_u64 v[4:5], v[0:1], 0, s[4:5]
	s_add_i32 m0, s27, 0x6400
	s_mov_b64 s[4:5], 0x120800
	global_load_lds_dwordx4 v[4:5], off
	v_lshl_add_u64 v[4:5], v[0:1], 0, s[4:5]
	s_add_i32 m0, s27, 0x6800
	s_mov_b64 s[4:5], 0x120c00
	global_load_lds_dwordx4 v[4:5], off
	v_lshl_add_u64 v[0:1], v[0:1], 0, s[4:5]
	s_add_i32 m0, s27, 0x6c00
	s_mov_b64 s[4:5], 0x10000
	global_load_lds_dwordx4 v[0:1], off
	v_lshl_add_u64 v[0:1], v[2:3], 0, s[4:5]
	s_add_i32 m0, s28, 0xa000
	s_mov_b64 s[4:5], 0x10400
	global_load_lds_dwordx4 v[0:1], off
	v_lshl_add_u64 v[0:1], v[2:3], 0, s[4:5]
	s_add_i32 m0, s28, 0xa400
	s_add_u32 s4, s22, s8
	global_load_lds_dwordx4 v[0:1], off
	s_addc_u32 s5, s23, s9
	s_add_u32 s6, s68, s6
	v_mov_b32_e32 v0, 0
	s_addc_u32 s7, s69, s7
	s_mov_b32 s29, 2
	v_mov_b32_e32 v1, v0
	v_mov_b32_e32 v2, v0
	v_mov_b32_e32 v3, v0
	v_mov_b32_e32 v4, v0
	v_mov_b32_e32 v5, v0
	v_mov_b32_e32 v6, v0
	v_mov_b32_e32 v7, v0
	v_mov_b32_e32 v8, v0
	v_mov_b32_e32 v9, v0
	v_mov_b32_e32 v10, v0
	v_mov_b32_e32 v11, v0
	v_mov_b32_e32 v12, v0
	v_mov_b32_e32 v13, v0
	v_mov_b32_e32 v14, v0
	v_mov_b32_e32 v15, v0
	v_mov_b32_e32 v16, v0
	v_mov_b32_e32 v17, v0
	v_mov_b32_e32 v18, v0
	v_mov_b32_e32 v19, v0
	v_mov_b32_e32 v20, v0
	v_mov_b32_e32 v21, v0
	v_mov_b32_e32 v22, v0
	v_mov_b32_e32 v23, v0
	v_mov_b32_e32 v24, v0
	v_mov_b32_e32 v25, v0
	v_mov_b32_e32 v26, v0
	v_mov_b32_e32 v27, v0
	v_mov_b32_e32 v28, v0
	v_mov_b32_e32 v29, v0
	v_mov_b32_e32 v30, v0
	v_mov_b32_e32 v31, v0
	v_mov_b32_e32 v32, v0
	v_mov_b32_e32 v33, v0
	v_mov_b32_e32 v34, v0
	v_mov_b32_e32 v35, v0
	v_mov_b32_e32 v36, v0
	v_mov_b32_e32 v37, v0
	v_mov_b32_e32 v38, v0
	v_mov_b32_e32 v39, v0
	v_mov_b32_e32 v40, v0
	v_mov_b32_e32 v41, v0
	v_mov_b32_e32 v42, v0
	v_mov_b32_e32 v43, v0
	v_mov_b32_e32 v44, v0
	v_mov_b32_e32 v45, v0
	v_mov_b32_e32 v46, v0
	v_mov_b32_e32 v47, v0
	v_mov_b32_e32 v48, v0
	v_mov_b32_e32 v49, v0
	v_mov_b32_e32 v50, v0
	v_mov_b32_e32 v51, v0
	v_mov_b32_e32 v52, v0
	v_mov_b32_e32 v53, v0
	v_mov_b32_e32 v54, v0
	v_mov_b32_e32 v55, v0
	v_mov_b32_e32 v56, v0
	v_mov_b32_e32 v57, v0
	v_mov_b32_e32 v58, v0
	v_mov_b32_e32 v59, v0
	v_mov_b32_e32 v60, v0
	v_mov_b32_e32 v61, v0
	v_mov_b32_e32 v62, v0
	v_mov_b32_e32 v63, v0
	v_mov_b32_e32 v64, v0
	v_mov_b32_e32 v65, v0
	v_mov_b32_e32 v66, v0
	v_mov_b32_e32 v67, v0
	v_mov_b32_e32 v68, v0
	v_mov_b32_e32 v69, v0
	v_mov_b32_e32 v70, v0
	v_mov_b32_e32 v71, v0
	v_mov_b32_e32 v72, v0
	v_mov_b32_e32 v73, v0
	v_mov_b32_e32 v74, v0
	v_mov_b32_e32 v75, v0
	v_mov_b32_e32 v76, v0
	v_mov_b32_e32 v77, v0
	v_mov_b32_e32 v78, v0
	v_mov_b32_e32 v79, v0
	v_mov_b32_e32 v80, v0
	v_mov_b32_e32 v81, v0
	v_mov_b32_e32 v82, v0
	v_mov_b32_e32 v83, v0
	v_mov_b32_e32 v84, v0
	v_mov_b32_e32 v85, v0
	v_mov_b32_e32 v86, v0
	v_mov_b32_e32 v87, v0
	v_mov_b32_e32 v88, v0
	v_mov_b32_e32 v89, v0
	v_mov_b32_e32 v90, v0
	v_mov_b32_e32 v91, v0
	v_mov_b32_e32 v92, v0
	v_mov_b32_e32 v93, v0
	v_mov_b32_e32 v94, v0
	v_mov_b32_e32 v95, v0
	v_mov_b32_e32 v96, v0
	v_mov_b32_e32 v97, v0
	v_mov_b32_e32 v98, v0
	v_mov_b32_e32 v99, v0
	v_mov_b32_e32 v100, v0
	v_mov_b32_e32 v101, v0
	v_mov_b32_e32 v102, v0
	v_mov_b32_e32 v103, v0
	v_mov_b32_e32 v104, v0
	v_mov_b32_e32 v105, v0
	v_mov_b32_e32 v106, v0
	v_mov_b32_e32 v107, v0
	v_mov_b32_e32 v108, v0
	v_mov_b32_e32 v109, v0
	v_mov_b32_e32 v110, v0
	v_mov_b32_e32 v111, v0
	v_mov_b32_e32 v112, v0
	v_mov_b32_e32 v113, v0
	v_mov_b32_e32 v114, v0
	v_mov_b32_e32 v115, v0
	v_mov_b32_e32 v116, v0
	v_mov_b32_e32 v117, v0
	v_mov_b32_e32 v118, v0
	v_mov_b32_e32 v119, v0
	v_mov_b32_e32 v120, v0
	v_mov_b32_e32 v121, v0
	v_mov_b32_e32 v122, v0
	v_mov_b32_e32 v123, v0
	v_mov_b32_e32 v124, v0
	v_mov_b32_e32 v125, v0
	v_mov_b32_e32 v126, v0
	v_mov_b32_e32 v127, v0
	v_mov_b32_e32 v129, v128
	v_mov_b32_e32 v130, v128
	v_mov_b32_e32 v131, v128
	v_mov_b32_e32 v136, v128
	v_mov_b32_e32 v137, v128
	v_mov_b32_e32 v138, v128
	v_mov_b32_e32 v139, v128
	v_mov_b32_e32 v140, v128
	v_mov_b32_e32 v141, v128
	v_mov_b32_e32 v142, v128
	v_mov_b32_e32 v143, v128
	v_mov_b32_e32 v148, v128
	v_mov_b32_e32 v149, v128
	v_mov_b32_e32 v150, v128
	v_mov_b32_e32 v151, v128
	v_mov_b32_e32 v132, v128
	v_mov_b32_e32 v133, v128
	v_mov_b32_e32 v134, v128
	v_mov_b32_e32 v135, v128
	v_mov_b32_e32 v144, v128
	v_mov_b32_e32 v145, v128
	v_mov_b32_e32 v146, v128
	v_mov_b32_e32 v147, v128
	s_branch .LBB0_1056
	s_nop 0

; #define RAW_BARRIER() do { asm volatile("s_waitcnt lgkmcnt(0)" ::: "memory"); __builtin_amdgcn_s_barrier(); } while (0)
; #define GEMM_READ4(A_, B_, FA, FB) asm volatile( \
;         "ds_read_b128 %0, %6\n\tds_read_b128 %1, %6 offset:2048\n\tds_read_b128 %2, %6 offset:4096\n\tds_read_b128 %3, %6 offset:6144\n\t" \
;         "ds_read_b128 %4, %7\n\tds_read_b128 %5, %7 offset:2048" \
;         : "=&v"(FA[0]), "=&v"(FA[1]), "=&v"(FA[2]), "=&v"(FA[3]), "=&v"(FB[0]), "=&v"(FB[1]) : "v"(A_), "v"(B_) : "memory")
; #define GEMM_READ2(A_, B_, FA, FB) asm volatile( \
;         "ds_read_b128 %0, %4\n\tds_read_b128 %1, %4 offset:2048\n\tds_read_b128 %2, %5\n\tds_read_b128 %3, %5 offset:2048" \
;         : "=&v"(FA[0]), "=&v"(FA[1]), "=&v"(FB[0]), "=&v"(FB[1]) : "v"(A_), "v"(B_) : "memory")
; #define GEMM_WAIT4(FA, FB) asm volatile("s_waitcnt lgkmcnt(0)" : "+v"(FA[0]), "+v"(FA[1]), "+v"(FA[2]), "+v"(FA[3]), "+v"(FB[0]), "+v"(FB[1]) :: "memory")
; #define GEMM_WAIT2(FA, FB) asm volatile("s_waitcnt lgkmcnt(0)" : "+v"(FA[0]), "+v"(FA[1]), "+v"(FB[0]), "+v"(FB[1]) :: "memory")
; template <int WM, class Epi>
; DI void gemm_mfma(const bf16_t* __restrict__ A, const bf16_t* __restrict__ Bt, int Arows, int Brows, int MT, int NT, unsigned char* smem, int bid, int nb, int wave, Epi epi) {
;     ...
; #pragma unroll 1
;     for (int kt = 0; kt < NKT; ++kt) {
;       const int ahead = (NKT - 1 - kt < NST - 2) ? (NKT - 1 - kt) : (NST - 2);
;       if (NI == 4) { if (ahead == 2) asm volatile("s_waitcnt vmcnt(8)" ::: "memory"); else if (ahead == 1) asm volatile("s_waitcnt vmcnt(4)" ::: "memory"); else asm volatile("s_waitcnt vmcnt(0)" ::: "memory"); }
;       else { if (ahead == 1) asm volatile("s_waitcnt vmcnt(6)" ::: "memory"); else asm volatile("s_waitcnt vmcnt(0)" ::: "memory"); }
;       RAW_BARRIER();
;       if (kt + NST - 1 < NKT) issue(kt + NST - 1, (kt + NST - 1) % NST);
;       const unsigned sb = lds0 + (unsigned)((kt % NST) * STAGE);
;       const unsigned a0 = sb + offA0, a1 = sb + offA1, b0 = sb + offB0, b1 = sb + offB1;
;       if constexpr (WM == 4) GEMM_READ4(a0, b0, fa0, fb0); else GEMM_READ2(a0, b0, fa0, fb0);
;       GEMM_MMA(fa1, fb1);
;       if constexpr (WM == 4) { GEMM_WAIT4(fa0, fb0); GEMM_READ4(a1, b1, fa1, fb1); } else { GEMM_WAIT2(fa0, fb0); GEMM_READ2(a1, b1, fa1, fb1); }
;       GEMM_MMA(fa0, fb0);
;     }
.LBB0_1060:
	s_waitcnt lgkmcnt(0)
	s_add_i32 s8, s29, -2
	s_cmp_gt_u32 s8, 29
	s_barrier
	s_cbranch_scc1 .LBB0_1055
	s_setprio 1
	v_mfma_f32_32x32x16_bf16 v[112:127], v[148:151], v[144:147], v[112:127]
	s_mul_i32 s9, s29, 0xab
	s_bfe_u32 s9, s9, 0x70009
	s_mul_i32 s9, s9, 3
	s_sub_i32 s9, s29, s9
	s_and_b32 s9, s9, 0xff
	s_mulk_i32 s9, 0x6000
	s_add_i32 s30, s9, s27
	s_add_i32 s9, s9, s28
	s_mul_i32 s34, s8, 0xab
	s_bfe_u32 s34, s34, 0x70009
	s_mul_i32 s34, s34, 3
	s_sub_i32 s8, s8, s34
	s_and_b32 s8, s8, 0xff
	s_mulk_i32 s8, 0x6000
	v_add_u32_e32 v216, s8, v157
	v_add_u32_e32 v217, s8, v159
	ds_read_b128 v[168:171], v216
	ds_read_b128 v[196:199], v216 offset:2048
	v_mfma_f32_32x32x16_bf16 v[96:111], v[148:151], v[132:135], v[96:111]
	ds_read_b128 v[200:203], v216 offset:4096
	ds_read_b128 v[204:207], v216 offset:6144
	v_mfma_f32_32x32x16_bf16 v[80:95], v[140:143], v[144:147], v[80:95]
	ds_read_b128 v[208:211], v217
	ds_read_b128 v[212:215], v217 offset:2048
	s_add_u32 s98, s4, 0x11a0000
	s_addc_u32 s99, s5, 0
	s_add_u32 s100, s6, 0x2006000
	s_addc_u32 s101, s7, 0
	s_add_i32 m0, s9, 0x4000
	v_mfma_f32_32x32x16_bf16 v[64:79], v[140:143], v[132:135], v[64:79]
	global_load_lds_dwordx4 v152, s[98:99]
	v_add_u32_e32 v216, s8, v158
	v_add_u32_e32 v217, s8, v164
	v_mfma_f32_32x32x16_bf16 v[48:63], v[136:139], v[144:147], v[48:63]
	global_load_lds_dwordx4 v152, s[98:99] offset:1024
	s_mov_b32 m0, s30
	v_mfma_f32_32x32x16_bf16 v[32:47], v[136:139], v[132:135], v[32:47]
	v_mfma_f32_32x32x16_bf16 v[16:31], v[128:131], v[144:147], v[16:31]
	global_load_lds_dwordx4 v152, s[100:101]
	v_mfma_f32_32x32x16_bf16 v[0:15], v[128:131], v[132:135], v[0:15]
	global_load_lds_dwordx4 v152, s[100:101] offset:1024
	s_setprio 0
	s_waitcnt lgkmcnt(0)
	ds_read_b128 v[148:151], v216
	ds_read_b128 v[140:143], v216 offset:2048
	ds_read_b128 v[136:139], v216 offset:4096
	ds_read_b128 v[128:131], v216 offset:6144
	ds_read_b128 v[144:147], v217
	ds_read_b128 v[132:135], v217 offset:2048
	s_setprio 1
	v_mfma_f32_32x32x16_bf16 v[112:127], v[168:171], v[208:211], v[112:127]
	global_load_lds_dwordx4 v152, s[100:101] offset:2048
	v_mfma_f32_32x32x16_bf16 v[96:111], v[168:171], v[212:215], v[96:111]
	v_mfma_f32_32x32x16_bf16 v[80:95], v[196:199], v[208:211], v[80:95]
	global_load_lds_dwordx4 v152, s[100:101] offset:3072
	v_mfma_f32_32x32x16_bf16 v[64:79], v[196:199], v[212:215], v[64:79]
	v_mfma_f32_32x32x16_bf16 v[48:63], v[200:203], v[208:211], v[48:63]
	v_mfma_f32_32x32x16_bf16 v[32:47], v[200:203], v[212:215], v[32:47]
	v_mfma_f32_32x32x16_bf16 v[16:31], v[204:207], v[208:211], v[16:31]
	v_mfma_f32_32x32x16_bf16 v[0:15], v[204:207], v[212:215], v[0:15]
	s_setprio 0
	s_add_u32 s4, s4, 0x10000
	s_addc_u32 s5, s5, 0
	s_add_u32 s6, s6, 0x120000
	s_addc_u32 s7, s7, 0
	s_add_i32 s29, s29, 1
	s_branch .LBB0_1056
	s_nop 0
